# gMLP units: next unit's 25 global loads prefetched into spare VGPRs during the current unit (moves at unit top), on top of v054
# baseline (speedup 1.0000x reference)
; __global__ void __launch_bounds__(NT, 2) fwd_mega(Args A) {
;     ...
; #pragma unroll 1
;     for (int u = vcu2; u < 1536; u += G) {
;         if (u < 512) attn_unit(PROJ, ws, lds, u);
;         else gmlp_unit(PROJ, ws, lds, u - 512);
;     }
.Lcvc_fin:
.Lcvc_end:
.LBB0_594:
	s_add_u32 s10, s28, 0x9900000
	s_addc_u32 s11, s29, 0
	s_add_u32 s20, s28, 0x40000
	s_addc_u32 s21, s29, 0
	s_cmpk_gt_i32 s96, 0x5ff
	s_cbranch_scc1 .LBB0_621
	s_add_u32 s42, s28, 0x1c0000
	s_addc_u32 s43, s29, 0
	s_add_u32 s47, s28, 0x200800
	s_addc_u32 s53, s29, 0
	v_mbcnt_hi_u32_b32 v167, -1, v161
	s_add_u32 s58, s28, 0x201800
	v_and_b32_e32 v0, 64, v167
	s_addc_u32 s59, s29, 0
	s_mov_b32 s45, 0
	v_mov_b32_e32 v163, 0
	s_movk_i32 s60, 0x1c00
	s_mov_b32 s46, 0x3a800000
	s_mov_b32 s61, 0xf800000
	v_mov_b32_e32 v166, 0x260
	s_movk_i32 s62, 0x120
	s_mov_b64 s[48:49], 0x9900800
	s_mov_b32 s63, 0x9900000
	s_movk_i32 s64, 0x110
	s_add_i32 s65, 0, 0x11000
	s_add_i32 s66, 0, 0x19800
	s_mov_b32 s67, 0xf149f2ca
	v_xor_b32_e32 v168, 16, v167
	v_add_u32_e32 v169, 64, v0
	v_xor_b32_e32 v170, 32, v167
	v_mov_b32_e32 v171, 0xf149f2ca
	s_mov_b32 s68, s96
	s_mov_b32 s74, 0
	s_branch .LBB0_598

; #define LAS __attribute__((address_space(3)))
; __device__ __forceinline__ void gmlp_unit(const bf16* proj, unsigned char* ws, LAS unsigned char* lds, int gu) {
;     ...
;     const int gb = gu >> 3, h = gu & 7, tok0 = gb * 128, fr = lane & 15, fq = lane >> 4;
;     LAS unsigned char* VN = lds;
;     const int c = tid & 15, r0 = tid >> 4;
;     v4u raw[4]; f32x2 stv[4];
;     tile_ld(raw, proj, tok0, C_VG + h * 128, tid);
; #pragma unroll
;     for (int p = 0; p < 4; ++p) stv[p] = *(const f32x2*)(lnstat + 2 * (tok0 + r0 + 32 * p));
;     const f32x4 g0 = *(const f32x4*)(par + PAR_GV + h * 128 + 8 * c), g1 = *(const f32x4*)(par + PAR_GV + h * 128 + 8 * c + 4);
;     const f32x4 b0 = *(const f32x4*)(par + PAR_BV + h * 128 + 8 * c), b1 = *(const f32x4*)(par + PAR_BV + h * 128 + 8 * c + 4);
;     bf16x8 wf[4];
; #pragma unroll
;     for (int s = 0; s < 4; ++s) wf[s] = *(const bf16x8*)(wsp + ((size_t)(h * 128 + 16 * wave + fr) * 128 + 32 * s + 8 * fq));
;     const int tok = tok0 + 16 * wave + fr; const float bsp = par[PAR_BSP + h * 128 + 16 * wave + fr];
;     const bf16* urow = proj + (size_t)tok * INW + C_U + h * 128 + 4 * fq; bf16* orow = mix + (size_t)tok * D + 1024 + h * 128 + 4 * fq;
;     v2u uw[8];
; #pragma unroll
;     for (int ct = 0; ct < 8; ++ct) uw[ct] = *(const v2u*)(urow + 16 * ct);
.LBB0_600:
	s_cmp_lg_u32 s74, 0
	s_cbranch_scc1 .Lgp_ready
	s_mov_b32 s75, s68
	s_add_i32 s76, s75, 0xfffffe00
	s_lshl_b32 s77, s76, 4
	s_and_b32 s77, s77, 0x3f80
	v_ashrrev_i32_e32 v196, 4, v160
	v_add_u32_e32 v197, s77, v196
	v_lshlrev_b32_e32 v198, 1, v197
	v_ashrrev_i32_e32 v199, 31, v198
	v_lshl_add_u64 v[198:199], v[198:199], 2, s[28:29]
	global_load_dwordx2 v[110:111], v[198:199], off
	s_lshl_b32 s76, s76, 7
	s_and_b32 s78, s76, 0x380
	s_add_i32 s79, s78, 0xa00
	global_load_dwordx2 v[112:113], v[198:199], off offset:256
	global_load_dwordx2 v[114:115], v[198:199], off offset:512
	global_load_dwordx2 v[116:117], v[198:199], off offset:768
	s_lshl_b32 s80, s79, 1
	v_lshlrev_b32_e32 v200, 4, v160
	s_add_u32 s80, s26, s80
	s_addc_u32 s81, s27, 0
	v_and_b32_e32 v200, 0xf0, v200
	v_mov_b32_e32 v201, 0
	s_lshl_b32 s82, s78, 2
	v_lshl_add_u64 v[202:203], s[80:81], 0, v[200:201]
	s_add_u32 s80, s47, s82
	s_addc_u32 s81, s53, 0
	v_and_b32_e32 v204, 15, v160
	v_add_u32_e32 v205, 32, v197
	v_add_u32_e32 v206, 64, v197
	v_add_u32_e32 v207, 0x60, v197
	v_mad_i64_i32 v[208:209], s[84:85], v197, s60, v[202:203]
	v_lshlrev_b32_e32 v210, 5, v204
	v_mad_i64_i32 v[212:213], s[84:85], v205, s60, v[202:203]
	v_mad_i64_i32 v[214:215], s[84:85], v206, s60, v[202:203]
	v_mad_i64_i32 v[202:203], s[84:85], v207, s60, v[202:203]
	global_load_dwordx4 v[118:121], v[208:209], off
	global_load_dwordx4 v[122:125], v[212:213], off
	global_load_dwordx4 v[126:129], v[214:215], off
	global_load_dwordx4 v[130:133], v[202:203], off
	global_load_dwordx4 v[134:137], v210, s[80:81] offset:16
	global_load_dwordx4 v[138:141], v210, s[80:81]
	s_add_u32 s80, s58, s82
	s_addc_u32 s81, s59, 0
	global_load_dwordx4 v[142:145], v210, s[80:81] offset:16
	global_load_dwordx4 v[146:149], v210, s[80:81]
	v_readfirstlane_b32 s83, v160
	s_ashr_i32 s83, s83, 2
	s_and_b32 s83, s83, -16
	s_add_i32 s76, s83, s77
	v_or_b32_e32 v205, s76, v204
	s_add_i32 s76, s83, s78
	s_add_i32 s83, s83, s79
	v_or_b32_e32 v206, s76, v204
	v_or_b32_e32 v208, s83, v204
	v_mov_b64_e32 v[212:213], s[26:27]
	v_ashrrev_i32_e32 v207, 31, v206
	v_bfe_u32 v196, v160, 4, 2
	s_lshl_b32 s86, s78, 1
	s_mov_b32 s87, 0
	v_mad_i64_i32 v[212:213], s[84:85], v205, s60, v[212:213]
	v_lshlrev_b64 v[206:207], 8, v[206:207]
	v_lshlrev_b32_e32 v214, 4, v196
	v_mov_b32_e32 v215, 0
	v_lshlrev_b32_e32 v200, 3, v196
	v_ashrrev_i32_e32 v209, 31, v208
	v_lshl_add_u64 v[212:213], v[212:213], 0, s[86:87]
	v_lshl_add_u64 v[206:207], s[42:43], 0, v[206:207]
	v_lshl_add_u64 v[208:209], v[208:209], 2, s[40:41]
	v_lshl_add_u64 v[212:213], v[212:213], 0, v[200:201]
	v_lshl_add_u64 v[206:207], v[206:207], 0, v[214:215]
	global_load_dword v150, v[208:209], off
	global_load_dwordx2 v[152:153], v[212:213], off offset:3072
	global_load_dwordx2 v[154:155], v[212:213], off offset:3104
	global_load_dwordx2 v[156:157], v[212:213], off offset:3136
	global_load_dwordx2 v[158:159], v[212:213], off offset:3168
	global_load_dwordx2 v[172:173], v[212:213], off offset:3200
	global_load_dwordx2 v[174:175], v[212:213], off offset:3232
	global_load_dwordx2 v[176:177], v[212:213], off offset:3264
	global_load_dwordx2 v[178:179], v[212:213], off offset:3296
	global_load_dwordx4 v[180:183], v[206:207], off
	global_load_dwordx4 v[184:187], v[206:207], off offset:64
	global_load_dwordx4 v[188:191], v[206:207], off offset:128
	global_load_dwordx4 v[192:195], v[206:207], off offset:192
	s_waitcnt vmcnt(0)
.Lgp_ready:
	s_waitcnt vmcnt(8)
	s_add_i32 s0, s68, 0xfffffe00
	v_mov_b32_e32 v41, v160
	s_lshl_b32 s1, s0, 4
	s_and_b32 s4, s1, 0x3f80
	v_ashrrev_i32_e32 v76, 4, v41
	v_add_u32_e32 v10, s4, v76
	v_lshlrev_b32_e32 v0, 1, v10
	s_waitcnt lgkmcnt(0)
	v_ashrrev_i32_e32 v1, 31, v0
	v_lshl_add_u64 v[0:1], v[0:1], 2, s[28:29]
	v_mov_b64_e32 v[8:9], v[110:111]
	s_lshl_b32 s0, s0, 7
	s_and_b32 s13, s0, 0x380
	s_add_i32 s50, s13, 0xa00
	v_mov_b64_e32 v[70:71], v[112:113]
	v_mov_b64_e32 v[72:73], v[114:115]
	v_mov_b64_e32 v[58:59], v[116:117]
	s_lshl_b32 s0, s50, 1
	v_lshlrev_b32_e32 v2, 4, v41
	s_add_u32 s0, s26, s0
	v_and_b32_e32 v162, 0xf0, v2
	s_addc_u32 s1, s27, 0
	s_lshl_b32 s44, s13, 2
	v_lshl_add_u64 v[6:7], s[0:1], 0, v[162:163]
	s_add_u32 s0, s47, s44
	v_and_b32_e32 v78, 15, v41
	v_add_u32_e32 v11, 32, v10
	v_add_u32_e32 v12, 64, v10
	v_add_u32_e32 v15, 0x60, v10
	v_mad_i64_i32 v[0:1], s[2:3], v10, s60, v[6:7]
	s_addc_u32 s1, s53, 0
	v_lshlrev_b32_e32 v14, 5, v78
	v_mad_i64_i32 v[10:11], s[2:3], v11, s60, v[6:7]
	v_mad_i64_i32 v[12:13], s[2:3], v12, s60, v[6:7]
	v_mad_i64_i32 v[6:7], s[2:3], v15, s60, v[6:7]
	v_mov_b64_e32 v[62:63], v[118:119]
	v_mov_b64_e32 v[64:65], v[120:121]
	v_mov_b64_e32 v[66:67], v[122:123]
	v_mov_b64_e32 v[68:69], v[124:125]
	v_mov_b64_e32 v[36:37], v[126:127]
	v_mov_b64_e32 v[38:39], v[128:129]
	v_mov_b64_e32 v[32:33], v[130:131]
	v_mov_b64_e32 v[34:35], v[132:133]
	v_mov_b64_e32 v[16:17], v[134:135]
	v_mov_b64_e32 v[18:19], v[136:137]
	v_mov_b64_e32 v[28:29], v[138:139]
	v_mov_b64_e32 v[30:31], v[140:141]
	s_add_u32 s0, s58, s44
	s_addc_u32 s1, s59, 0
	v_mov_b64_e32 v[20:21], v[142:143]
	v_mov_b64_e32 v[22:23], v[144:145]
	v_mov_b64_e32 v[24:25], v[146:147]
	v_mov_b64_e32 v[26:27], v[148:149]
	v_readfirstlane_b32 s5, v41
	s_ashr_i32 s2, s5, 2
	s_and_b32 s0, s2, -16
	s_add_i32 s2, s0, s4
	v_or_b32_e32 v40, s2, v78
	s_add_i32 s1, s0, s13
	s_add_i32 s0, s0, s50
	v_or_b32_e32 v0, s1, v78
	v_or_b32_e32 v6, s0, v78
	v_mov_b64_e32 v[4:5], s[26:27]
	v_ashrrev_i32_e32 v1, 31, v0
	v_bfe_u32 v60, v41, 4, 2
	s_lshl_b32 s44, s13, 1
	v_mad_i64_i32 v[4:5], s[0:1], v40, s60, v[4:5]
	v_lshlrev_b64 v[0:1], 8, v[0:1]
	v_mov_b32_e32 v3, v163
	v_lshlrev_b32_e32 v2, 4, v60
; __device__ __forceinline__ void gmlp_unit(const bf16* proj, unsigned char* ws, LAS unsigned char* lds, int gu) {
;     ...
;     const int c = tid & 15, r0 = tid >> 4;
;     v4u raw[4]; f32x2 stv[4];
;     tile_ld(raw, proj, tok0, C_VG + h * 128, tid);
; #pragma unroll
;     for (int p = 0; p < 4; ++p) stv[p] = *(const f32x2*)(lnstat + 2 * (tok0 + r0 + 32 * p));
;     const f32x4 g0 = *(const f32x4*)(par + PAR_GV + h * 128 + 8 * c), g1 = *(const f32x4*)(par + PAR_GV + h * 128 + 8 * c + 4);
;     const f32x4 b0 = *(const f32x4*)(par + PAR_BV + h * 128 + 8 * c), b1 = *(const f32x4*)(par + PAR_BV + h * 128 + 8 * c + 4);
;     bf16x8 wf[4];
; #pragma unroll
;     for (int s = 0; s < 4; ++s) wf[s] = *(const bf16x8*)(wsp + ((size_t)(h * 128 + 16 * wave + fr) * 128 + 32 * s + 8 * fq));
;     const int tok = tok0 + 16 * wave + fr; const float bsp = par[PAR_BSP + h * 128 + 16 * wave + fr];
;     const bf16* urow = proj + (size_t)tok * INW + C_U + h * 128 + 4 * fq; bf16* orow = mix + (size_t)tok * D + 1024 + h * 128 + 4 * fq;
;     v2u uw[8];
; #pragma unroll
;     for (int ct = 0; ct < 8; ++ct) uw[ct] = *(const v2u*)(urow + 16 * ct);
;     __syncthreads();
; #pragma unroll
;     for (int p = 0; p < 4; ++p) {
;         const float mu = stv[p][0] * (1.0f / 1024.0f), var = fmaxf(stv[p][1] * (1.0f / 1024.0f) - mu * mu, 0.f), rstd = 1.0f / sqrtf(var + pg8::EPSN);
	v_lshlrev_b32_e32 v162, 3, v60
	v_ashrrev_i32_e32 v7, 31, v6
	v_lshl_add_u64 v[4:5], v[4:5], 0, s[44:45]
	v_lshl_add_u64 v[0:1], s[42:43], 0, v[0:1]
	v_lshl_add_u64 v[6:7], v[6:7], 2, s[40:41]
	v_lshl_add_u64 v[4:5], v[4:5], 0, v[162:163]
	v_lshl_add_u64 v[10:11], v[0:1], 0, v[2:3]
	v_mov_b32_e32 v61, v150
	v_mov_b64_e32 v[56:57], v[152:153]
	v_mov_b64_e32 v[54:55], v[154:155]
	v_mov_b64_e32 v[52:53], v[156:157]
	v_mov_b64_e32 v[50:51], v[158:159]
	v_mov_b64_e32 v[48:49], v[172:173]
	v_mov_b64_e32 v[46:47], v[174:175]
	v_mov_b64_e32 v[44:45], v[176:177]
	v_mov_b64_e32 v[42:43], v[178:179]
	v_mov_b64_e32 v[0:1], v[180:181]
	v_mov_b64_e32 v[2:3], v[182:183]
	s_nop 0
	v_mov_b64_e32 v[4:5], v[184:185]
	v_mov_b64_e32 v[6:7], v[186:187]
	v_lshlrev_b32_e32 v78, 4, v78
	v_mul_lo_u32 v76, v76, s62
	v_add3_u32 v76, 0, v78, v76
	v_lshlrev_b32_e32 v77, 3, v41
	s_nop 0
	v_pk_mul_f32 v[74:75], v[8:9], s[46:47] op_sel_hi:[1,0]
	s_nop 0
	v_fma_f32 v8, -v74, v74, v75
	v_max_f32_e32 v8, 0, v8
	v_add_f32_e32 v8, 0x358637bd, v8
	v_mul_f32_e32 v9, 0x4f800000, v8
	v_cmp_gt_f32_e32 vcc, s61, v8
	s_nop 0
	v_pk_mul_f32 v[70:71], v[70:71], s[46:47] op_sel_hi:[1,0]
	s_nop 0
	v_pk_mul_f32 v[58:59], v[58:59], s[46:47] op_sel_hi:[1,0]
	v_cndmask_b32_e32 v75, v8, v9, vcc
	v_sqrt_f32_e32 v79, v75
	v_fma_f32 v71, -v70, v70, v71
	v_max_f32_e32 v71, 0, v71
	v_add_f32_e32 v71, 0x358637bd, v71
	v_add_u32_e32 v80, -1, v79
	v_fma_f32 v81, -v80, v79, v75
	v_cmp_ge_f32_e64 s[2:3], 0, v81
	v_add_u32_e32 v81, 1, v79
	v_mov_b64_e32 v[12:13], v[188:189]
	v_mov_b64_e32 v[14:15], v[190:191]
	s_nop 0
	v_mov_b64_e32 v[8:9], v[192:193]
	v_mov_b64_e32 v[10:11], v[194:195]
	s_add_i32 s75, s68, s30
	s_mov_b32 s74, 0
	s_cmpk_gt_i32 s75, 0x5ff
	s_cbranch_scc1 .Lgp_nopf
	s_mov_b32 s74, 1
	s_add_i32 s76, s75, 0xfffffe00
	s_lshl_b32 s77, s76, 4
	s_and_b32 s77, s77, 0x3f80
	v_ashrrev_i32_e32 v196, 4, v160
	v_add_u32_e32 v197, s77, v196
	v_lshlrev_b32_e32 v198, 1, v197
	v_ashrrev_i32_e32 v199, 31, v198
	v_lshl_add_u64 v[198:199], v[198:199], 2, s[28:29]
	global_load_dwordx2 v[110:111], v[198:199], off
	s_lshl_b32 s76, s76, 7
	s_and_b32 s78, s76, 0x380
	s_add_i32 s79, s78, 0xa00
	global_load_dwordx2 v[112:113], v[198:199], off offset:256
	global_load_dwordx2 v[114:115], v[198:199], off offset:512
	global_load_dwordx2 v[116:117], v[198:199], off offset:768
	s_lshl_b32 s80, s79, 1
	v_lshlrev_b32_e32 v200, 4, v160
	s_add_u32 s80, s26, s80
	s_addc_u32 s81, s27, 0
	v_and_b32_e32 v200, 0xf0, v200
	v_mov_b32_e32 v201, 0
	s_lshl_b32 s82, s78, 2
	v_lshl_add_u64 v[202:203], s[80:81], 0, v[200:201]
	s_add_u32 s80, s47, s82
	s_addc_u32 s81, s53, 0
	v_and_b32_e32 v204, 15, v160
	v_add_u32_e32 v205, 32, v197
	v_add_u32_e32 v206, 64, v197
	v_add_u32_e32 v207, 0x60, v197
	v_mad_i64_i32 v[208:209], s[84:85], v197, s60, v[202:203]
	v_lshlrev_b32_e32 v210, 5, v204
	v_mad_i64_i32 v[212:213], s[84:85], v205, s60, v[202:203]
	v_mad_i64_i32 v[214:215], s[84:85], v206, s60, v[202:203]
	v_mad_i64_i32 v[202:203], s[84:85], v207, s60, v[202:203]
	global_load_dwordx4 v[118:121], v[208:209], off
	global_load_dwordx4 v[122:125], v[212:213], off
	global_load_dwordx4 v[126:129], v[214:215], off
	global_load_dwordx4 v[130:133], v[202:203], off
	global_load_dwordx4 v[134:137], v210, s[80:81] offset:16
	global_load_dwordx4 v[138:141], v210, s[80:81]
	s_add_u32 s80, s58, s82
	s_addc_u32 s81, s59, 0
	global_load_dwordx4 v[142:145], v210, s[80:81] offset:16
	global_load_dwordx4 v[146:149], v210, s[80:81]
	v_readfirstlane_b32 s83, v160
	s_ashr_i32 s83, s83, 2
	s_and_b32 s83, s83, -16
	s_add_i32 s76, s83, s77
	v_or_b32_e32 v205, s76, v204
	s_add_i32 s76, s83, s78
	s_add_i32 s83, s83, s79
	v_or_b32_e32 v206, s76, v204
	v_or_b32_e32 v208, s83, v204
	v_mov_b64_e32 v[212:213], s[26:27]
	v_ashrrev_i32_e32 v207, 31, v206
	v_bfe_u32 v196, v160, 4, 2
	s_lshl_b32 s86, s78, 1
	s_mov_b32 s87, 0
	v_mad_i64_i32 v[212:213], s[84:85], v205, s60, v[212:213]
	v_lshlrev_b64 v[206:207], 8, v[206:207]
	v_lshlrev_b32_e32 v214, 4, v196
	v_mov_b32_e32 v215, 0
	v_lshlrev_b32_e32 v200, 3, v196
	v_ashrrev_i32_e32 v209, 31, v208
	v_lshl_add_u64 v[212:213], v[212:213], 0, s[86:87]
	v_lshl_add_u64 v[206:207], s[42:43], 0, v[206:207]
	v_lshl_add_u64 v[208:209], v[208:209], 2, s[40:41]
	v_lshl_add_u64 v[212:213], v[212:213], 0, v[200:201]
	v_lshl_add_u64 v[206:207], v[206:207], 0, v[214:215]
	global_load_dword v150, v[208:209], off
	global_load_dwordx2 v[152:153], v[212:213], off offset:3072
	global_load_dwordx2 v[154:155], v[212:213], off offset:3104
	global_load_dwordx2 v[156:157], v[212:213], off offset:3136
	global_load_dwordx2 v[158:159], v[212:213], off offset:3168
	global_load_dwordx2 v[172:173], v[212:213], off offset:3200
	global_load_dwordx2 v[174:175], v[212:213], off offset:3232
	global_load_dwordx2 v[176:177], v[212:213], off offset:3264
	global_load_dwordx2 v[178:179], v[212:213], off offset:3296
	global_load_dwordx4 v[180:183], v[206:207], off
	global_load_dwordx4 v[184:187], v[206:207], off offset:64
	global_load_dwordx4 v[188:191], v[206:207], off offset:128
	global_load_dwordx4 v[192:195], v[206:207], off offset:192
; #define LAS __attribute__((address_space(3)))
; __device__ __forceinline__ unsigned pk2(float lo, float hi) { return pg8::cvt_pk_bf16(lo, hi); }
; __device__ __forceinline__ void gmlp_unit(const bf16* proj, unsigned char* ws, LAS unsigned char* lds, int gu) {
;     ...
; #pragma unroll
;     for (int p = 0; p < 4; ++p) {
;         const float mu = stv[p][0] * (1.0f / 1024.0f), var = fmaxf(stv[p][1] * (1.0f / 1024.0f) - mu * mu, 0.f), rstd = 1.0f / sqrtf(var + pg8::EPSN);
;         float v[8];
;         v[0] = bflo(raw[p].x); v[1] = bfhi(raw[p].x); v[2] = bflo(raw[p].y); v[3] = bfhi(raw[p].y); v[4] = bflo(raw[p].z); v[5] = bfhi(raw[p].z); v[6] = bflo(raw[p].w); v[7] = bfhi(raw[p].w);
; #pragma unroll
;         for (int e = 0; e < 4; ++e) { v[e] = (v[e] - mu) * rstd * g0[e] + b0[e]; v[4 + e] = (v[4 + e] - mu) * rstd * g1[e] + b1[e]; }
;         v4u o; o.x = pk2(v[0], v[1]); o.y = pk2(v[2], v[3]); o.z = pk2(v[4], v[5]); o.w = pk2(v[6], v[7]);
;         *(LAS v4u*)(VN + (r0 + 32 * p) * V_STRIDE + c * 16) = o;
;     }
.Lgp_nopf:
	v_cndmask_b32_e64 v80, v79, v80, s[2:3]
	v_fma_f32 v79, -v81, v79, v75
	v_cmp_lt_f32_e64 s[2:3], 0, v79
	s_barrier
	s_nop 0
	v_cndmask_b32_e64 v79, v80, v81, s[2:3]
	v_mul_f32_e32 v80, 0x37800000, v79
	v_cndmask_b32_e32 v79, v79, v80, vcc
	v_cmp_class_f32_e32 vcc, v75, v166
	v_fma_f32 v59, -v58, v58, v59
	s_nop 0
	v_cndmask_b32_e32 v75, v79, v75, vcc
	v_div_scale_f32 v79, s[0:1], v75, v75, 1.0
	v_rcp_f32_e32 v80, v79
	v_max_f32_e32 v59, 0, v59
	v_add_f32_e32 v59, 0x358637bd, v59
	v_fma_f32 v81, -v79, v80, 1.0
	v_fmac_f32_e32 v80, v81, v80
	v_div_scale_f32 v81, vcc, 1.0, v75, 1.0
	v_mul_f32_e32 v82, v81, v80
	v_fma_f32 v83, -v79, v82, v81
	v_fmac_f32_e32 v82, v83, v80
	v_fma_f32 v79, -v79, v82, v81
	v_div_fmas_f32 v79, v79, v80, v82
	v_div_fixup_f32 v75, v79, v75, 1.0
	s_nop 0
	v_lshlrev_b32_e32 v79, 16, v62
	v_and_b32_e32 v62, 0xffff0000, v62
	v_lshlrev_b32_e32 v80, 16, v63
	v_and_b32_e32 v63, 0xffff0000, v63
	v_lshlrev_b32_e32 v81, 16, v64
	v_and_b32_e32 v64, 0xffff0000, v64
	v_lshlrev_b32_e32 v82, 16, v65
	v_and_b32_e32 v65, 0xffff0000, v65
	v_sub_f32_e32 v79, v79, v74
	v_sub_f32_e32 v81, v81, v74
	v_sub_f32_e32 v62, v62, v74
	v_sub_f32_e32 v64, v64, v74
	v_sub_f32_e32 v80, v80, v74
	v_sub_f32_e32 v82, v82, v74
	v_sub_f32_e32 v63, v63, v74
	v_sub_f32_e32 v65, v65, v74
	v_mul_f32_e32 v74, 0x4f800000, v71
	v_cmp_gt_f32_e32 vcc, s61, v71
	v_mul_f32_e32 v79, v79, v75
	v_mul_f32_e32 v62, v62, v75
	v_cndmask_b32_e32 v71, v71, v74, vcc
	v_sqrt_f32_e32 v74, v71
	s_nop 0
	v_fma_f32 v79, v28, v79, v24
	v_mul_f32_e32 v81, v81, v75
	v_fma_f32 v62, v29, v62, v25
	v_mul_f32_e32 v64, v64, v75
	v_mul_f32_e32 v80, v80, v75
	v_mul_f32_e32 v82, v82, v75
	v_mul_f32_e32 v63, v63, v75
	v_mul_f32_e32 v65, v65, v75
	v_add_u32_e32 v75, -1, v74
	v_cvt_pk_bf16_f32 v62, v79, v62
	v_fma_f32 v79, -v75, v74, v71
	v_cmp_ge_f32_e64 s[2:3], 0, v79
	v_add_u32_e32 v79, 1, v74
	v_fma_f32 v64, v17, v64, v21
	v_cndmask_b32_e64 v75, v74, v75, s[2:3]
	v_fma_f32 v74, -v79, v74, v71
	v_cmp_lt_f32_e64 s[2:3], 0, v74
	v_fma_f32 v63, v31, v63, v27
	v_fma_f32 v65, v19, v65, v23
	v_cndmask_b32_e64 v74, v75, v79, s[2:3]
	v_mul_f32_e32 v75, 0x37800000, v74
	v_cndmask_b32_e32 v74, v74, v75, vcc
	v_cmp_class_f32_e32 vcc, v71, v166
	v_fma_f32 v81, v16, v81, v20
	v_fma_f32 v80, v30, v80, v26
	v_cndmask_b32_e32 v71, v74, v71, vcc
	v_div_scale_f32 v74, s[0:1], v71, v71, 1.0
	v_rcp_f32_e32 v75, v74
	v_fma_f32 v82, v18, v82, v22
	v_cvt_pk_bf16_f32 v63, v80, v63
	v_cvt_pk_bf16_f32 v64, v81, v64
	v_cvt_pk_bf16_f32 v65, v82, v65
	ds_write_b128 v76, v[62:65]
	v_fma_f32 v62, -v74, v75, 1.0
	v_fmac_f32_e32 v75, v62, v75
	v_div_scale_f32 v62, vcc, 1.0, v71, 1.0
	v_mul_f32_e32 v63, v62, v75
	v_fma_f32 v64, -v74, v63, v62
	v_fmac_f32_e32 v63, v64, v75
	v_fma_f32 v62, -v74, v63, v62
	v_div_fmas_f32 v62, v62, v75, v63
	v_lshlrev_b32_e32 v63, 16, v66
	v_and_b32_e32 v64, 0xffff0000, v66
	v_lshlrev_b32_e32 v65, 16, v67
	v_and_b32_e32 v66, 0xffff0000, v67
	v_lshlrev_b32_e32 v67, 16, v68
	v_div_fixup_f32 v62, v62, v71, 1.0
	v_sub_f32_e32 v67, v67, v70
	v_and_b32_e32 v68, 0xffff0000, v68
	v_mul_f32_e32 v67, v67, v62
	v_fma_f32 v74, v16, v67, v20
	v_sub_f32_e32 v67, v68, v70
	v_lshlrev_b32_e32 v71, 16, v69
	v_mul_f32_e32 v67, v67, v62
	v_sub_f32_e32 v66, v66, v70
	v_and_b32_e32 v69, 0xffff0000, v69
	v_fma_f32 v68, v17, v67, v21
	v_sub_f32_e32 v67, v71, v70
	v_mul_f32_e32 v66, v66, v62
	v_sub_f32_e32 v63, v63, v70
	v_sub_f32_e32 v64, v64, v70
	v_sub_f32_e32 v65, v65, v70
	v_mul_f32_e32 v67, v67, v62
	v_fma_f32 v75, v31, v66, v27
	v_sub_f32_e32 v66, v69, v70
	v_mul_f32_e32 v63, v63, v62
	v_mul_f32_e32 v64, v64, v62
	v_mul_f32_e32 v65, v65, v62
	v_fma_f32 v71, v18, v67, v22
	v_mul_f32_e32 v62, v66, v62
	v_pk_mul_f32 v[66:67], v[72:73], s[46:47] op_sel_hi:[1,0]
	v_fma_f32 v64, v29, v64, v25
	v_fma_f32 v67, -v66, v66, v67
	v_max_f32_e32 v67, 0, v67
	v_add_f32_e32 v67, 0x358637bd, v67
	v_mul_f32_e32 v69, 0x4f800000, v67
	v_cmp_gt_f32_e32 vcc, s61, v67
	v_fma_f32 v63, v28, v63, v24
	v_fma_f32 v65, v30, v65, v26
	v_cndmask_b32_e32 v67, v67, v69, vcc
	v_sqrt_f32_e32 v69, v67
	v_fma_f32 v70, v19, v62, v23
	v_cvt_pk_bf16_f32 v62, v63, v64
	v_cvt_pk_bf16_f32 v63, v65, v75
	v_add_u32_e32 v64, -1, v69
	v_fma_f32 v65, -v64, v69, v67
	v_cmp_ge_f32_e64 s[2:3], 0, v65
	v_add_u32_e32 v65, 1, v69
	s_nop 0
	v_cndmask_b32_e64 v64, v69, v64, s[2:3]
	v_fma_f32 v69, -v65, v69, v67
	v_cmp_lt_f32_e64 s[2:3], 0, v69
	s_nop 1
	v_cndmask_b32_e64 v64, v64, v65, s[2:3]
	v_mul_f32_e32 v65, 0x37800000, v64
	v_cndmask_b32_e32 v64, v64, v65, vcc
	v_cmp_class_f32_e32 vcc, v67, v166
	s_nop 1
	v_cndmask_b32_e32 v67, v64, v67, vcc
	v_div_scale_f32 v69, s[0:1], v67, v67, 1.0
	v_rcp_f32_e32 v72, v69
	v_cvt_pk_bf16_f32 v64, v74, v68
	v_cvt_pk_bf16_f32 v65, v71, v70
	ds_write_b128 v76, v[62:65] offset:9216
	v_fma_f32 v62, -v69, v72, 1.0
	v_fmac_f32_e32 v72, v62, v72
	v_div_scale_f32 v62, vcc, 1.0, v67, 1.0
	v_mul_f32_e32 v63, v62, v72
	v_fma_f32 v64, -v69, v63, v62
	v_fmac_f32_e32 v63, v64, v72
	v_fma_f32 v62, -v69, v63, v62
	v_div_fmas_f32 v62, v62, v72, v63
	v_div_fixup_f32 v62, v62, v67, 1.0
	v_lshlrev_b32_e32 v63, 16, v36
	v_and_b32_e32 v36, 0xffff0000, v36
	v_lshlrev_b32_e32 v64, 16, v37
	v_and_b32_e32 v37, 0xffff0000, v37
	v_lshlrev_b32_e32 v65, 16, v38
	v_and_b32_e32 v38, 0xffff0000, v38
	v_lshlrev_b32_e32 v67, 16, v39
	v_and_b32_e32 v39, 0xffff0000, v39
	v_sub_f32_e32 v63, v63, v66
	v_sub_f32_e32 v65, v65, v66
	v_sub_f32_e32 v36, v36, v66
	v_sub_f32_e32 v38, v38, v66
	v_sub_f32_e32 v64, v64, v66
	v_sub_f32_e32 v67, v67, v66
	v_sub_f32_e32 v37, v37, v66
	v_sub_f32_e32 v39, v39, v66
	v_mul_f32_e32 v63, v63, v62
	v_mul_f32_e32 v65, v65, v62
; #define LAS __attribute__((address_space(3)))
; __device__ __forceinline__ unsigned pk2(float lo, float hi) { return pg8::cvt_pk_bf16(lo, hi); }
; __device__ __forceinline__ void gmlp_unit(const bf16* proj, unsigned char* ws, LAS unsigned char* lds, int gu) {
;     ...
;     for (int p = 0; p < 4; ++p) {
;         const float mu = stv[p][0] * (1.0f / 1024.0f), var = fmaxf(stv[p][1] * (1.0f / 1024.0f) - mu * mu, 0.f), rstd = 1.0f / sqrtf(var + pg8::EPSN);
;         float v[8];
;         v[0] = bflo(raw[p].x); v[1] = bfhi(raw[p].x); v[2] = bflo(raw[p].y); v[3] = bfhi(raw[p].y); v[4] = bflo(raw[p].z); v[5] = bfhi(raw[p].z); v[6] = bflo(raw[p].w); v[7] = bfhi(raw[p].w);
; #pragma unroll
;         for (int e = 0; e < 4; ++e) { v[e] = (v[e] - mu) * rstd * g0[e] + b0[e]; v[4 + e] = (v[4 + e] - mu) * rstd * g1[e] + b1[e]; }
;         v4u o; o.x = pk2(v[0], v[1]); o.y = pk2(v[2], v[3]); o.z = pk2(v[4], v[5]); o.w = pk2(v[6], v[7]);
;         *(LAS v4u*)(VN + (r0 + 32 * p) * V_STRIDE + c * 16) = o;
;     }
;     __syncthreads();
;     f32x4 acc[8];
; #pragma unroll
;     for (int ct = 0; ct < 8; ++ct) {
;         acc[ct] = (f32x4){0.f, 0.f, 0.f, 0.f};
; #pragma unroll
;         for (int s = 0; s < 4; ++s) {
;             const LAS unsigned char* p0 = VN + (32 * s + 8 * fq + (fr >> 2)) * V_STRIDE + (16 * ct + 4 * (fr & 3)) * 2;
;             const bf16x8 vf = tr_frag(p0, p0 + 4 * V_STRIDE);
;             acc[ct] = __builtin_amdgcn_mfma_f32_16x16x32_bf16(vf, wf[s], acc[ct], 0, 0, 0);
;         }
;     }
	v_mul_f32_e32 v36, v36, v62
	v_mul_f32_e32 v38, v38, v62
	v_mul_f32_e32 v64, v64, v62
	v_mul_f32_e32 v67, v67, v62
	v_mul_f32_e32 v37, v37, v62
	v_mul_f32_e32 v39, v39, v62
	v_mul_f32_e32 v62, 0x4f800000, v59
	v_cmp_gt_f32_e32 vcc, s61, v59
	v_fma_f32 v63, v28, v63, v24
	v_fma_f32 v36, v29, v36, v25
	v_cndmask_b32_e32 v59, v59, v62, vcc
	v_sqrt_f32_e32 v62, v59
	v_fma_f32 v64, v30, v64, v26
	v_fma_f32 v37, v31, v37, v27
	v_cvt_pk_bf16_f32 v36, v63, v36
	v_add_u32_e32 v63, -1, v62
	v_cvt_pk_bf16_f32 v37, v64, v37
	v_fma_f32 v64, -v63, v62, v59
	v_cmp_ge_f32_e64 s[2:3], 0, v64
	v_add_u32_e32 v64, 1, v62
	v_fma_f32 v38, v17, v38, v21
	v_cndmask_b32_e64 v63, v62, v63, s[2:3]
	v_fma_f32 v62, -v64, v62, v59
	v_cmp_lt_f32_e64 s[2:3], 0, v62
	v_fma_f32 v39, v19, v39, v23
	v_fma_f32 v65, v16, v65, v20
	v_cndmask_b32_e64 v62, v63, v64, s[2:3]
	v_mul_f32_e32 v63, 0x37800000, v62
	v_cndmask_b32_e32 v62, v62, v63, vcc
	v_cmp_class_f32_e32 vcc, v59, v166
	v_fma_f32 v67, v18, v67, v22
	v_cvt_pk_bf16_f32 v38, v65, v38
	v_cvt_pk_bf16_f32 v39, v67, v39
	ds_write_b128 v76, v[36:39] offset:18432
	v_cndmask_b32_e32 v59, v62, v59, vcc
	v_div_scale_f32 v62, s[0:1], v59, v59, 1.0
	v_rcp_f32_e32 v63, v62
	v_lshlrev_b32_e32 v39, 16, v34
	v_and_b32_e32 v34, 0xffff0000, v34
	v_fma_f32 v36, -v62, v63, 1.0
	v_fmac_f32_e32 v63, v36, v63
	v_div_scale_f32 v36, vcc, 1.0, v59, 1.0
	v_mul_f32_e32 v37, v36, v63
	v_fma_f32 v38, -v62, v37, v36
	v_fmac_f32_e32 v37, v38, v63
	v_fma_f32 v36, -v62, v37, v36
	v_div_fmas_f32 v36, v36, v63, v37
	v_lshlrev_b32_e32 v37, 16, v32
	v_div_fixup_f32 v36, v36, v59, 1.0
	v_sub_f32_e32 v37, v37, v58
	v_mul_f32_e32 v37, v37, v36
	v_fma_f32 v24, v28, v37, v24
	v_sub_f32_e32 v28, v39, v58
	v_and_b32_e32 v32, 0xffff0000, v32
	v_mul_f32_e32 v28, v28, v36
	v_fma_f32 v20, v16, v28, v20
	v_sub_f32_e32 v16, v32, v58
	v_mul_f32_e32 v16, v16, v36
	v_fma_f32 v16, v29, v16, v25
	v_sub_f32_e32 v25, v34, v58
	v_lshlrev_b32_e32 v59, 16, v35
	v_mul_f32_e32 v25, v25, v36
	v_fma_f32 v21, v17, v25, v21
	v_sub_f32_e32 v25, v59, v58
	v_lshlrev_b32_e32 v38, 16, v33
	v_and_b32_e32 v33, 0xffff0000, v33
	v_mul_f32_e32 v25, v25, v36
	v_fma_f32 v22, v18, v25, v22
	v_sub_f32_e32 v18, v33, v58
	v_and_b32_e32 v35, 0xffff0000, v35
	v_sub_f32_e32 v17, v38, v58
	v_mul_f32_e32 v18, v18, v36
	v_mul_f32_e32 v17, v17, v36
	v_fmac_f32_e32 v27, v31, v18
	v_sub_f32_e32 v18, v35, v58
	v_fma_f32 v17, v30, v17, v26
	v_mul_f32_e32 v18, v18, v36
	v_cvt_pk_bf16_f32 v16, v24, v16
	v_fmac_f32_e32 v23, v19, v18
	v_cvt_pk_bf16_f32 v17, v17, v27
	v_cvt_pk_bf16_f32 v18, v20, v21
	v_cvt_pk_bf16_f32 v19, v22, v23
	ds_write_b128 v76, v[16:19] offset:27648
	v_bfe_u32 v16, v41, 2, 2
	v_or_b32_e32 v16, v162, v16
	v_and_b32_e32 v17, 24, v77
	v_mul_u32_u24_e32 v16, 0x120, v16
	v_add3_u32 v41, 0, v17, v16
	s_waitcnt lgkmcnt(0)
	s_barrier
	ds_read_b64_tr_b16 v[18:19], v41 offset:1152
	ds_read_b64_tr_b16 v[16:17], v41
	ds_read_b64_tr_b16 v[20:21], v41 offset:9216
	ds_read_b64_tr_b16 v[22:23], v41 offset:10368
	ds_read_b64_tr_b16 v[24:25], v41 offset:32
	ds_read_b64_tr_b16 v[28:29], v41 offset:64
	ds_read_b64_tr_b16 v[32:33], v41 offset:96
	ds_read_b64_tr_b16 v[26:27], v41 offset:1184
	ds_read_b64_tr_b16 v[30:31], v41 offset:1216
	ds_read_b64_tr_b16 v[34:35], v41 offset:1248
	s_waitcnt lgkmcnt(2)
	v_mfma_f32_16x16x32_bf16 v[24:27], v[24:27], v[0:3], 0
	ds_read_b64_tr_b16 v[36:37], v41 offset:9248
	ds_read_b64_tr_b16 v[62:63], v41 offset:9280
	ds_read_b64_tr_b16 v[66:67], v41 offset:9312
	ds_read_b64_tr_b16 v[38:39], v41 offset:10400
	ds_read_b64_tr_b16 v[64:65], v41 offset:10432
	ds_read_b64_tr_b16 v[68:69], v41 offset:10464
	v_mfma_f32_16x16x32_bf16 v[16:19], v[16:19], v[0:3], 0
	s_waitcnt lgkmcnt(2)
	v_mfma_f32_16x16x32_bf16 v[24:27], v[36:39], v[4:7], v[24:27]
	v_mfma_f32_16x16x32_bf16 v[16:19], v[20:23], v[4:7], v[16:19]
	ds_read_b64_tr_b16 v[20:21], v41 offset:18432
	ds_read_b64_tr_b16 v[22:23], v41 offset:19584
	ds_read_b64_tr_b16 v[70:71], v41 offset:27648
	ds_read_b64_tr_b16 v[72:73], v41 offset:28800
	ds_read_b64_tr_b16 v[74:75], v41 offset:18464
	ds_read_b64_tr_b16 v[78:79], v41 offset:18496
	ds_read_b64_tr_b16 v[82:83], v41 offset:18528
	ds_read_b64_tr_b16 v[76:77], v41 offset:19616
	ds_read_b64_tr_b16 v[80:81], v41 offset:19648
	ds_read_b64_tr_b16 v[84:85], v41 offset:19680
	s_waitcnt lgkmcnt(2)
	v_mfma_f32_16x16x32_bf16 v[24:27], v[74:77], v[12:15], v[24:27]
	v_mfma_f32_16x16x32_bf16 v[16:19], v[20:23], v[12:15], v[16:19]
	ds_read_b64_tr_b16 v[20:21], v41 offset:27680
	ds_read_b64_tr_b16 v[86:87], v41 offset:27712
	ds_read_b64_tr_b16 v[90:91], v41 offset:27744
	ds_read_b64_tr_b16 v[22:23], v41 offset:28832
	ds_read_b64_tr_b16 v[88:89], v41 offset:28864
	ds_read_b64_tr_b16 v[92:93], v41 offset:28896
	s_waitcnt lgkmcnt(2)
	v_mfma_f32_16x16x32_bf16 v[20:23], v[20:23], v[8:11], v[24:27]
	v_mfma_f32_16x16x32_bf16 v[24:27], v[28:31], v[0:3], 0
	v_mfma_f32_16x16x32_bf16 v[28:31], v[32:35], v[0:3], 0
	v_mfma_f32_16x16x32_bf16 v[16:19], v[70:73], v[8:11], v[16:19]
	v_mfma_f32_16x16x32_bf16 v[24:27], v[62:65], v[4:7], v[24:27]
	v_mfma_f32_16x16x32_bf16 v[28:31], v[66:69], v[4:7], v[28:31]
	ds_read_b64_tr_b16 v[32:33], v41 offset:128
	ds_read_b64_tr_b16 v[34:35], v41 offset:1280
	ds_read_b64_tr_b16 v[36:37], v41 offset:9344
	ds_read_b64_tr_b16 v[38:39], v41 offset:10496
	ds_read_b64_tr_b16 v[62:63], v41 offset:160
	ds_read_b64_tr_b16 v[66:67], v41 offset:192
	ds_read_b64_tr_b16 v[70:71], v41 offset:224
	ds_read_b64_tr_b16 v[64:65], v41 offset:1312
	ds_read_b64_tr_b16 v[68:69], v41 offset:1344
	ds_read_b64_tr_b16 v[72:73], v41 offset:1376
	s_waitcnt lgkmcnt(2)
; #define LAS __attribute__((address_space(3)))
; __device__ __forceinline__ void gmlp_unit(const bf16* proj, unsigned char* ws, LAS unsigned char* lds, int gu) {
;     ...
;     f32x4 acc[8];
; #pragma unroll
;     for (int ct = 0; ct < 8; ++ct) {
;         acc[ct] = (f32x4){0.f, 0.f, 0.f, 0.f};
; #pragma unroll
;         for (int s = 0; s < 4; ++s) {
;             const LAS unsigned char* p0 = VN + (32 * s + 8 * fq + (fr >> 2)) * V_STRIDE + (16 * ct + 4 * (fr & 3)) * 2;
;             const bf16x8 vf = tr_frag(p0, p0 + 4 * V_STRIDE);
;             acc[ct] = __builtin_amdgcn_mfma_f32_16x16x32_bf16(vf, wf[s], acc[ct], 0, 0, 0);
;         }
;     }
;     float ss = 0.f;
; #pragma unroll
;     for (int ct = 0; ct < 8; ++ct) {
;         const float o0 = bflo(uw[ct].x) * (acc[ct][0] + bsp), o1 = bfhi(uw[ct].x) * (acc[ct][1] + bsp), o2 = bflo(uw[ct].y) * (acc[ct][2] + bsp), o3 = bfhi(uw[ct].y) * (acc[ct][3] + bsp);
	v_mfma_f32_16x16x32_bf16 v[62:65], v[62:65], v[0:3], 0
	v_mfma_f32_16x16x32_bf16 v[24:27], v[78:81], v[12:15], v[24:27]
	v_mfma_f32_16x16x32_bf16 v[28:31], v[82:85], v[12:15], v[28:31]
	ds_read_b64_tr_b16 v[74:75], v41 offset:9376
	ds_read_b64_tr_b16 v[78:79], v41 offset:9408
	ds_read_b64_tr_b16 v[82:83], v41 offset:9440
	ds_read_b64_tr_b16 v[76:77], v41 offset:10528
	ds_read_b64_tr_b16 v[80:81], v41 offset:10560
	ds_read_b64_tr_b16 v[84:85], v41 offset:10592
	v_mfma_f32_16x16x32_bf16 v[32:35], v[32:35], v[0:3], 0
	s_waitcnt lgkmcnt(2)
	v_mfma_f32_16x16x32_bf16 v[62:65], v[74:77], v[4:7], v[62:65]
	v_mfma_f32_16x16x32_bf16 v[24:27], v[86:89], v[8:11], v[24:27]
	v_mfma_f32_16x16x32_bf16 v[28:31], v[90:93], v[8:11], v[28:31]
	v_mfma_f32_16x16x32_bf16 v[32:35], v[36:39], v[4:7], v[32:35]
	ds_read_b64_tr_b16 v[36:37], v41 offset:18560
	ds_read_b64_tr_b16 v[38:39], v41 offset:19712
	ds_read_b64_tr_b16 v[86:87], v41 offset:27776
	ds_read_b64_tr_b16 v[88:89], v41 offset:28928
	ds_read_b64_tr_b16 v[90:91], v41 offset:18592
	ds_read_b64_tr_b16 v[94:95], v41 offset:18624
	ds_read_b64_tr_b16 v[98:99], v41 offset:18656
	ds_read_b64_tr_b16 v[92:93], v41 offset:19744
	ds_read_b64_tr_b16 v[96:97], v41 offset:19776
	ds_read_b64_tr_b16 v[100:101], v41 offset:19808
	s_waitcnt lgkmcnt(2)
	v_mfma_f32_16x16x32_bf16 v[62:65], v[90:93], v[12:15], v[62:65]
	v_mfma_f32_16x16x32_bf16 v[32:35], v[36:39], v[12:15], v[32:35]
	ds_read_b64_tr_b16 v[36:37], v41 offset:27808
	ds_read_b64_tr_b16 v[102:103], v41 offset:27840
	ds_read_b64_tr_b16 v[106:107], v41 offset:27872
	ds_read_b64_tr_b16 v[38:39], v41 offset:28960
	ds_read_b64_tr_b16 v[104:105], v41 offset:28992
	ds_read_b64_tr_b16 v[108:109], v41 offset:29024
	v_ashrrev_i32_e32 v41, 31, v40
	s_waitcnt lgkmcnt(2)
	v_mfma_f32_16x16x32_bf16 v[36:39], v[36:39], v[8:11], v[62:65]
	v_mfma_f32_16x16x32_bf16 v[62:65], v[66:69], v[0:3], 0
	v_mfma_f32_16x16x32_bf16 v[0:3], v[70:73], v[0:3], 0
	v_mfma_f32_16x16x32_bf16 v[62:65], v[78:81], v[4:7], v[62:65]
	v_mfma_f32_16x16x32_bf16 v[0:3], v[82:85], v[4:7], v[0:3]
	v_lshlrev_b64 v[4:5], 12, v[40:41]
	v_lshl_add_u64 v[4:5], s[28:29], 0, v[4:5]
	v_lshl_add_u64 v[4:5], v[4:5], 0, s[44:45]
	v_mfma_f32_16x16x32_bf16 v[62:65], v[94:97], v[12:15], v[62:65]
	v_lshl_add_u64 v[4:5], v[4:5], 0, v[162:163]
	v_lshl_add_u64 v[6:7], v[4:5], 0, s[48:49]
	v_add_co_u32_e32 v4, vcc, s63, v4
	v_mfma_f32_16x16x32_bf16 v[0:3], v[98:101], v[12:15], v[0:3]
	v_add_f32_e32 v12, v61, v19
	v_addc_co_u32_e32 v5, vcc, 0, v5, vcc
	v_mfma_f32_16x16x32_bf16 v[32:35], v[86:89], v[8:11], v[32:35]
	v_cmp_lt_i32_e32 vcc, v168, v169
	s_waitcnt lgkmcnt(1)
	v_mfma_f32_16x16x32_bf16 v[62:65], v[102:105], v[8:11], v[62:65]
	s_waitcnt lgkmcnt(0)
; __device__ __forceinline__ unsigned pk2(float lo, float hi) { return pg8::cvt_pk_bf16(lo, hi); }
; __device__ __forceinline__ void gmlp_unit(const bf16* proj, unsigned char* ws, LAS unsigned char* lds, int gu) {
;     ...
;     float ss = 0.f;
; #pragma unroll
;     for (int ct = 0; ct < 8; ++ct) {
;         const float o0 = bflo(uw[ct].x) * (acc[ct][0] + bsp), o1 = bfhi(uw[ct].x) * (acc[ct][1] + bsp), o2 = bflo(uw[ct].y) * (acc[ct][2] + bsp), o3 = bfhi(uw[ct].y) * (acc[ct][3] + bsp);
;         ss += (o0 * o0 + o1 * o1) + (o2 * o2 + o3 * o3);
;         v2u w; w.x = pk2(o0, o1); w.y = pk2(o2, o3); *(v2u*)(orow + 16 * ct) = w;
;     }
;     ss += __shfl_xor(ss, 16); ss += __shfl_xor(ss, 32);
;     if (fq == 0) unsafeAtomicAdd(ssmix + (size_t)tok * 2 + 1, ss);
	v_mfma_f32_16x16x32_bf16 v[0:3], v[106:109], v[8:11], v[0:3]
	v_lshlrev_b32_e32 v8, 16, v56
	v_add_f32_e32 v9, v61, v16
	v_mul_f32_e32 v8, v9, v8
	v_and_b32_e32 v9, 0xffff0000, v56
	v_add_f32_e32 v10, v61, v17
	v_mul_f32_e32 v9, v10, v9
	v_lshlrev_b32_e32 v10, 16, v57
	v_add_f32_e32 v11, v61, v18
	v_mul_f32_e32 v10, v11, v10
	v_and_b32_e32 v11, 0xffff0000, v57
	v_mul_f32_e32 v11, v12, v11
	v_mul_f32_e32 v12, v9, v9
	v_fmac_f32_e32 v12, v8, v8
	v_cvt_pk_bf16_f32 v8, v8, v9
	v_cvt_pk_bf16_f32 v9, v10, v11
	global_store_dwordx2 v[4:5], v[8:9], off offset:2048
	v_lshlrev_b32_e32 v4, 16, v54
	v_add_f32_e32 v5, v61, v20
	v_mul_f32_e32 v4, v5, v4
	v_and_b32_e32 v5, 0xffff0000, v54
	v_add_f32_e32 v8, v61, v21
	v_mul_f32_e32 v13, v11, v11
	v_mul_f32_e32 v5, v8, v5
	v_lshlrev_b32_e32 v8, 16, v55
	v_add_f32_e32 v9, v61, v22
	v_fmac_f32_e32 v13, v10, v10
	v_mul_f32_e32 v8, v9, v8
	v_and_b32_e32 v9, 0xffff0000, v55
	v_add_f32_e32 v10, v61, v23
	v_mul_f32_e32 v9, v10, v9
	v_mul_f32_e32 v10, v5, v5
	v_fmac_f32_e32 v10, v4, v4
	v_cvt_pk_bf16_f32 v4, v4, v5
	v_cvt_pk_bf16_f32 v5, v8, v9
	v_mul_f32_e32 v11, v9, v9
	global_store_dwordx2 v[6:7], v[4:5], off offset:32
	v_lshlrev_b32_e32 v4, 16, v52
	v_add_f32_e32 v5, v61, v24
	v_fmac_f32_e32 v11, v8, v8
	v_mul_f32_e32 v4, v5, v4
	v_and_b32_e32 v5, 0xffff0000, v52
	v_add_f32_e32 v8, v61, v25
	v_mul_f32_e32 v5, v8, v5
	v_lshlrev_b32_e32 v8, 16, v53
	v_add_f32_e32 v9, v61, v26
	v_add_f32_e32 v10, v10, v11
	v_mul_f32_e32 v8, v9, v8
	v_and_b32_e32 v9, 0xffff0000, v53
	v_add_f32_e32 v11, v61, v27
	v_mul_f32_e32 v9, v11, v9
	v_mul_f32_e32 v11, v5, v5
	v_add_f32_e32 v12, v12, v13
	v_fmac_f32_e32 v11, v4, v4
	v_cvt_pk_bf16_f32 v4, v4, v5
	v_cvt_pk_bf16_f32 v5, v8, v9
	v_add_f32_e32 v10, v12, v10
	v_mul_f32_e32 v12, v9, v9
	global_store_dwordx2 v[6:7], v[4:5], off offset:64
	v_lshlrev_b32_e32 v4, 16, v50
	v_add_f32_e32 v5, v61, v28
	v_fmac_f32_e32 v12, v8, v8
	v_mul_f32_e32 v4, v5, v4
	v_and_b32_e32 v5, 0xffff0000, v50
	v_add_f32_e32 v8, v61, v29
	v_add_f32_e32 v11, v11, v12
	v_mul_f32_e32 v5, v8, v5
	v_lshlrev_b32_e32 v8, 16, v51
	v_add_f32_e32 v9, v61, v30
	v_add_f32_e32 v10, v10, v11
	v_mul_f32_e32 v8, v9, v8
	v_and_b32_e32 v9, 0xffff0000, v51
	v_add_f32_e32 v11, v61, v31
	v_mul_f32_e32 v9, v11, v9
	v_mul_f32_e32 v11, v5, v5
	v_fmac_f32_e32 v11, v4, v4
	v_cvt_pk_bf16_f32 v4, v4, v5
	v_cvt_pk_bf16_f32 v5, v8, v9
	v_mul_f32_e32 v12, v9, v9
	global_store_dwordx2 v[6:7], v[4:5], off offset:96
	v_lshlrev_b32_e32 v4, 16, v48
	v_add_f32_e32 v5, v61, v32
	v_fmac_f32_e32 v12, v8, v8
	v_mul_f32_e32 v4, v5, v4
	v_and_b32_e32 v5, 0xffff0000, v48
	v_add_f32_e32 v8, v61, v33
	v_add_f32_e32 v11, v11, v12
	v_mul_f32_e32 v5, v8, v5
	v_lshlrev_b32_e32 v8, 16, v49
	v_add_f32_e32 v9, v61, v34
	v_add_f32_e32 v10, v10, v11
	v_mul_f32_e32 v8, v9, v8
	v_and_b32_e32 v9, 0xffff0000, v49
	v_add_f32_e32 v11, v61, v35
	v_mul_f32_e32 v9, v11, v9
	v_mul_f32_e32 v11, v5, v5
	v_fmac_f32_e32 v11, v4, v4
	v_cvt_pk_bf16_f32 v4, v4, v5
	v_cvt_pk_bf16_f32 v5, v8, v9
	v_mul_f32_e32 v12, v9, v9
	global_store_dwordx2 v[6:7], v[4:5], off offset:128
	v_lshlrev_b32_e32 v4, 16, v46
	v_add_f32_e32 v5, v61, v36
	v_fmac_f32_e32 v12, v8, v8
	v_mul_f32_e32 v4, v5, v4
	v_and_b32_e32 v5, 0xffff0000, v46
	v_add_f32_e32 v8, v61, v37
	v_add_f32_e32 v11, v11, v12
	v_mul_f32_e32 v5, v8, v5
	v_lshlrev_b32_e32 v8, 16, v47
	v_add_f32_e32 v9, v61, v38
	v_add_f32_e32 v10, v10, v11
	v_mul_f32_e32 v8, v9, v8
	v_and_b32_e32 v9, 0xffff0000, v47
	v_add_f32_e32 v11, v61, v39
	v_mul_f32_e32 v9, v11, v9
	v_mul_f32_e32 v11, v5, v5
	v_mul_f32_e32 v12, v9, v9
	v_fmac_f32_e32 v11, v4, v4
	v_fmac_f32_e32 v12, v8, v8
	v_add_f32_e32 v11, v11, v12
	v_cvt_pk_bf16_f32 v4, v4, v5
	v_cvt_pk_bf16_f32 v5, v8, v9
	v_lshlrev_b32_e32 v8, 16, v44
	v_add_f32_e32 v9, v61, v62
	v_add_f32_e32 v10, v10, v11
	v_mul_f32_e32 v8, v9, v8
	v_and_b32_e32 v9, 0xffff0000, v44
	v_add_f32_e32 v11, v61, v63
	v_mul_f32_e32 v9, v11, v9
	v_lshlrev_b32_e32 v11, 16, v45
	v_add_f32_e32 v12, v61, v64
	v_mul_f32_e32 v11, v12, v11
	v_and_b32_e32 v12, 0xffff0000, v45
	v_add_f32_e32 v13, v61, v65
	v_mul_f32_e32 v12, v13, v12
	v_mul_f32_e32 v13, v9, v9
	v_mul_f32_e32 v14, v12, v12
	v_fmac_f32_e32 v13, v8, v8
	v_fmac_f32_e32 v14, v11, v11
	v_add_f32_e32 v13, v13, v14
	v_add_f32_e32 v10, v10, v13
	v_lshlrev_b32_e32 v13, 16, v42
	v_add_f32_e32 v0, v61, v0
	v_mul_f32_e32 v13, v0, v13
	v_and_b32_e32 v0, 0xffff0000, v42
	v_add_f32_e32 v1, v61, v1
	v_mul_f32_e32 v14, v1, v0
	v_lshlrev_b32_e32 v0, 16, v43
	v_add_f32_e32 v1, v61, v2
	v_mul_f32_e32 v15, v1, v0
	v_and_b32_e32 v0, 0xffff0000, v43
	v_add_f32_e32 v1, v61, v3
	v_mul_f32_e32 v3, v1, v0
	v_mul_f32_e32 v0, v14, v14
	v_mul_f32_e32 v1, v3, v3
	v_fmac_f32_e32 v0, v13, v13
	v_fmac_f32_e32 v1, v15, v15
	v_add_f32_e32 v0, v0, v1
	v_add_f32_e32 v2, v10, v0
	v_cndmask_b32_e32 v0, v167, v168, vcc
	v_lshlrev_b32_e32 v0, 2, v0
	ds_bpermute_b32 v10, v0, v2
	global_store_dwordx2 v[6:7], v[4:5], off offset:160
	v_cvt_pk_bf16_f32 v0, v8, v9
	v_cvt_pk_bf16_f32 v1, v11, v12
	v_cmp_lt_i32_e32 vcc, v170, v169
	global_store_dwordx2 v[6:7], v[0:1], off offset:192
	s_waitcnt lgkmcnt(0)
	v_add_f32_e32 v0, v2, v10
	v_cndmask_b32_e32 v1, v167, v170, vcc
	v_lshlrev_b32_e32 v1, 2, v1
	ds_bpermute_b32 v1, v1, v0
	v_cmp_eq_u32_e32 vcc, 0, v60
	v_cvt_pk_bf16_f32 v2, v13, v14
	v_cvt_pk_bf16_f32 v3, v15, v3
	global_store_dwordx2 v[6:7], v[2:3], off offset:224
	s_and_saveexec_b64 s[2:3], vcc
	s_cbranch_execz .LBB0_602
	s_waitcnt lgkmcnt(0)
	v_add_f32_e32 v2, v0, v1
	v_lshl_add_u64 v[0:1], v[40:41], 3, s[28:29]
	v_add_co_u32_e32 v0, vcc, 0x40000, v0
	s_nop 1
	v_addc_co_u32_e32 v1, vcc, 0, v1, vcc
	global_atomic_add_f32 v[0:1], v2, off offset:4
